# negm plus padding so that every GEMM K-loop head sits at 4 mod 8 and the attention loop head at 56 mod 64
# baseline (speedup 1.0000x reference)
; __device__ __forceinline__ void xcd_barrier_complete(unsigned* bar, unsigned x, unsigned& nloc, unsigned& nx) {
;     const unsigned G = gridDim.x * gridDim.y * gridDim.z;
;     unsigned sum, cnt, mine, sp = 0u;
;     for (;;) {
;         sum = 0u; cnt = 0u; mine = 0u;
; #pragma unroll
; __device__ __forceinline__ void xcd_barrier(const XcdBarrier& b) {
;     asm volatile("s_waitcnt vmcnt(0)" ::: "memory");
;     __syncthreads();
;     if (threadIdx.x == 0) {
;         unsigned* bar = b.bar;
;         __builtin_amdgcn_s_waitcnt(0);
;         unsigned nloc = b.st[0], nx = b.st[1];
;         if (nloc == 0u) { xcd_barrier_complete(bar, b.x, nloc, nx); b.st[0] = nloc; b.st[1] = nx; }
.LBB0_373:
	s_waitcnt vmcnt(0)
	s_waitcnt lgkmcnt(0)
	s_barrier
	s_nop 0
	s_mov_b64 s[4:5], exec
	v_readlane_b32 s6, v254, 5
	v_readlane_b32 s7, v254, 6
	v_readlane_b32 s28, v254, 1
	s_and_b64 s[6:7], s[4:5], s[6:7]
	v_readlane_b32 s29, v254, 2
	s_mov_b64 exec, s[6:7]
	s_cbranch_execz .LBB0_425
	s_add_i32 s1, 0, 0x20000
	v_mov_b32_e32 v0, s1
	s_waitcnt vmcnt(0) expcnt(0) lgkmcnt(0)
	ds_read_b32 v2, v0
	s_add_i32 s1, 0, 0x20004
	v_mov_b32_e32 v0, s1
	ds_read_b32 v0, v0
	s_waitcnt lgkmcnt(1)
	v_cmp_ne_u32_e32 vcc, 0, v2
	s_cbranch_vccnz .LBB0_389
	s_add_u32 s6, s44, 0x1000
	s_addc_u32 s7, s45, 0
	s_add_u32 s8, s44, 0x1100
	s_addc_u32 s9, s45, 0
	s_add_u32 s10, s44, 0x1200
	v_readlane_b32 s1, v254, 0
	s_addc_u32 s11, s45, 0
	s_mul_i32 s1, s41, s1
	s_add_u32 s12, s44, 0x1300
	s_mul_i32 s1, s1, s40
	s_addc_u32 s13, s45, 0
	s_mov_b32 s3, 1
	v_mov_b32_e32 v16, 0
	s_branch .LBB0_377
